# v12 + rout unit order: pass0 chunks 0-31 of all heads, pass1 chunks 32-63
# baseline (speedup 1.0000x reference)
; __device__ __forceinline__ void ret_out_phase(LAS unsigned char* lds, const bf16* PROJ, const bf16* KVT, const bf16* ST, bf16* Y, float* RN, int G, int bid) {
;     ...
;     for (int u = bid; u < 512; u += G) {
;         asm volatile("" : "+v"(tid_));
;         const int tid = tid_, lane = tid & 63, w = __builtin_amdgcn_readfirstlane(tid >> 6), g = lane >> 4, li = lane & 15;
.LBB0_100:
	s_andn2_b64 vcc, exec, s[0:1]
	s_cbranch_vccnz .LBB0_175
	v_readlane_b32 s0, v250, 7
	v_readlane_b32 s1, v250, 8
	v_mov_b32_e32 v111, v183
	s_andn2_b64 vcc, exec, s[0:1]
	s_cbranch_vccnz .LBB0_175
	v_readlane_b32 s20, v250, 0
	s_mov_b32 s16, s20
	s_mov_b32 s98, s20
	v_readlane_b32 s17, v250, 31
	s_branch .LBB0_105

; #define LAS __attribute__((address_space(3)))
; #define RO_WRITE(rv, rs, buf) do { _Pragma("unroll") for (int i = 0; i < 2; ++i) { const int q = tid + 512 * i; *(LAS v4u*)(lds + (buf) + (q >> 4) * VROW + (q & 15) * 16) = rv[i]; } \
;             if (cross) { _Pragma("unroll") for (int i = 0; i < 4; ++i) { const int q = tid + 512 * i; *(LAS v4u*)(lds + (buf) + VTB + (q >> 5) * SROW + (q & 31) * 16) = rs[i]; } } } while (0)
; __device__ __forceinline__ void ret_out_phase(LAS unsigned char* lds, const bf16* PROJ, const bf16* KVT, const bf16* ST, bf16* Y, float* RN, int G, int bid) {
;     ...
;     for (int u = bid; u < 512; u += G) {
;         asm volatile("" : "+v"(tid_));
;         const int tid = tid_, lane = tid & 63, w = __builtin_amdgcn_readfirstlane(tid >> 6), g = lane >> 4, li = lane & 15;
;         const int h = u >> 6, c = u & 63, t0 = c * 128, n0 = 16 * w;
;         const bool cross = (c > 0);
;         bf16x8 qf[8];
; #pragma unroll
;         for (int ks = 0; ks < 8; ++ks) qf[ks] = *(const bf16x8*)(PROJ + (size_t)(t0 + n0 + li) * 6144 + h * 256 + 32 * ks + 8 * g);
;         {
;             v4u rk[8];
; #pragma unroll
;             for (int i = 0; i < 8; ++i) { const int q = tid + 512 * i; rk[i] = *(const v4u*)(KVT + (size_t)(h * 256 + (q >> 4)) * KVT_LD + t0 + (q & 15) * 8); }
; #pragma unroll
;             for (int i = 0; i < 8; ++i) { const int q = tid + 512 * i; *(LAS v4u*)(lds + KS + (q >> 4) * KROW + (q & 15) * 16) = rk[i]; }
;         }
;         v4u rvA[2], rsA[4];
;     ...
;         RO_LOAD(rvA, rsA, 0); RO_WRITE(rvA, rsA, BUF0);
.LBB0_104:
	s_or_b64 exec, exec, s[4:5]
	s_waitcnt lgkmcnt(0)
	s_barrier
	s_add_i32 s98, s98, s90
	s_cmpk_gt_i32 s98, 0x1ff
	s_cbranch_scc1 .LBB0_175
.LBB0_105:
	s_lshr_b32 s20, s98, 5
	s_and_b32 s20, s20, 7
	s_lshl_b32 s20, s20, 6
	s_and_b32 s16, s98, 31
	s_or_b32 s20, s20, s16
	s_lshr_b32 s16, s98, 8
	s_lshl_b32 s16, s16, 5
	s_or_b32 s20, s20, s16
	s_mov_b32 s16, s20
	s_lshl_b32 s17, s20, 9
	s_and_b32 s3, s20, 63
	v_readfirstlane_b32 s0, v111
	s_ashr_i32 s1, s0, 6
	s_lshl_b32 s0, s3, 7
	s_lshl_b32 s10, s1, 4
	v_and_b32_e32 v98, 15, v111
	s_add_i32 s0, s10, s0
	v_or_b32_e32 v2, s0, v98
	s_waitcnt lgkmcnt(0)
	v_mov_b64_e32 v[8:9], s[40:41]
	s_movk_i32 s0, 0x3000
	s_ashr_i32 s2, s20, 6
	v_mad_i64_i32 v[8:9], s[4:5], v2, s0, v[8:9]
	s_lshl_b32 s4, s2, 8
	s_ashr_i32 s5, s4, 31
	s_lshl_b32 s0, s3, 8
	v_readlane_b32 s12, v253, 22
	v_readlane_b32 s13, v253, 23
	s_add_u32 s12, s12, s0
	v_lshlrev_b32_e32 v101, 4, v111
	s_addc_u32 s13, s13, 0
	v_and_b32_e32 v94, 0xf0, v101
	v_mov_b32_e32 v95, v1
	v_ashrrev_i32_e32 v99, 4, v111
	v_add_u32_e32 v82, 0x200, v111
	v_lshl_add_u64 v[108:109], s[12:13], 0, v[94:95]
	v_add_u32_e32 v3, s4, v99
	s_movk_i32 s22, 0x4080
	v_ashrrev_i32_e32 v100, 4, v82
	v_mad_i64_i32 v[56:57], s[12:13], v3, s22, v[108:109]
	v_add_u32_e32 v3, s4, v100
	v_lshl_add_u64 v[8:9], s[4:5], 1, v[8:9]
	v_and_b32_e32 v0, 48, v111
	v_mad_i64_i32 v[60:61], s[12:13], v3, s22, v[108:109]
	v_add_u32_e32 v3, 0x400, v111
	v_lshl_add_u64 v[36:37], v[8:9], 0, v[0:1]
	v_ashrrev_i32_e32 v65, 4, v3
	v_add_u32_e32 v88, 0x600, v111
	global_load_dwordx4 v[8:11], v[36:37], off
	global_load_dwordx4 v[12:15], v[36:37], off offset:64
	global_load_dwordx4 v[16:19], v[36:37], off offset:128
	global_load_dwordx4 v[20:23], v[36:37], off offset:192
	global_load_dwordx4 v[24:27], v[36:37], off offset:256
	global_load_dwordx4 v[28:31], v[36:37], off offset:320
	global_load_dwordx4 v[32:35], v[36:37], off offset:384
	s_nop 0
	global_load_dwordx4 v[36:39], v[36:37], off offset:448
	v_add_u32_e32 v66, s4, v65
	global_load_dwordx4 v[56:59], v[56:57], off
	v_ashrrev_i32_e32 v83, 4, v88
	s_waitcnt vmcnt(0)
	v_add_u32_e32 v74, 0x800, v111
	v_mad_i64_i32 v[66:67], s[12:13], v66, s22, v[108:109]
	v_add_u32_e32 v70, s4, v83
	v_ashrrev_i32_e32 v89, 4, v74
	v_add_u32_e32 v78, 0xa00, v111
	global_load_dwordx4 v[60:63], v[60:61], off
	v_mad_i64_i32 v[70:71], s[12:13], v70, s22, v[108:109]
	global_load_dwordx4 v[66:69], v[66:67], off
	v_add_u32_e32 v74, s4, v89
	v_ashrrev_i32_e32 v95, 4, v78
	v_add_u32_e32 v84, 0xc00, v111
	global_load_dwordx4 v[70:73], v[70:71], off
	v_mad_i64_i32 v[74:75], s[12:13], v74, s22, v[108:109]
	v_add_u32_e32 v78, s4, v95
	v_ashrrev_i32_e32 v96, 4, v84
	global_load_dwordx4 v[74:77], v[74:75], off
	v_mad_i64_i32 v[78:79], s[12:13], v78, s22, v[108:109]
	v_add_u32_e32 v84, s4, v96
	v_add_u32_e32 v90, 0xe00, v111
	global_load_dwordx4 v[78:81], v[78:79], off
	v_mad_i64_i32 v[84:85], s[12:13], v84, s22, v[108:109]
	v_ashrrev_i32_e32 v97, 4, v90
	global_load_dwordx4 v[84:87], v[84:85], off
	v_add_u32_e32 v90, s4, v97
	v_mad_i64_i32 v[90:91], s[4:5], v90, s22, v[108:109]
	global_load_dwordx4 v[90:93], v[90:91], off
	s_movk_i32 s0, 0x110
	v_add_u32_e32 v94, 0, v94
	v_mul_lo_u32 v102, v99, s0
	v_add_u32_e32 v156, v94, v102
	v_lshlrev_b32_e32 v64, 3, v111
	s_movk_i32 s23, 0x110
	v_ashrrev_i32_e32 v104, 5, v111
	v_ashrrev_i32_e32 v105, 5, v82
	v_ashrrev_i32_e32 v106, 5, v3
	v_ashrrev_i32_e32 v107, 5, v88
	s_waitcnt vmcnt(7)
	ds_write_b128 v156, v[56:59] offset:51200
	v_mul_lo_u32 v56, v100, s0
	v_add_u32_e32 v157, v94, v56
	v_mad_u64_u32 v[56:57], s[4:5], v65, s0, v[94:95]
	s_waitcnt vmcnt(6)
	ds_write_b128 v157, v[60:63] offset:51200
	s_waitcnt vmcnt(5)
	ds_write_b128 v56, v[66:69] offset:51200
	v_mad_u64_u32 v[56:57], s[4:5], v83, s0, v[94:95]
	s_waitcnt vmcnt(4)
	ds_write_b128 v56, v[70:73] offset:51200
	v_mad_u64_u32 v[56:57], s[4:5], v89, s0, v[94:95]
	s_waitcnt vmcnt(3)
	ds_write_b128 v56, v[74:77] offset:51200
	v_mad_u64_u32 v[56:57], s[4:5], v95, s0, v[94:95]
	s_waitcnt vmcnt(2)
	ds_write_b128 v56, v[78:81] offset:51200
	v_mad_u64_u32 v[56:57], s[4:5], v96, s0, v[94:95]
	v_and_b32_e32 v96, 0xf8, v64
	s_waitcnt vmcnt(1)
	ds_write_b128 v56, v[84:87] offset:51200
	v_mad_u64_u32 v[56:57], s[4:5], v97, s0, v[94:95]
	s_lshl_b32 s0, s2, 9
	s_add_i32 s11, s0, 0x800
	s_waitcnt vmcnt(0)
	ds_write_b128 v56, v[90:93] offset:51200
	v_add_u32_e32 v56, s11, v99
	v_add_u32_e32 v60, s11, v100
	v_mad_i64_i32 v[56:57], s[4:5], v56, s22, v[108:109]
	v_mad_i64_i32 v[60:61], s[4:5], v60, s22, v[108:109]
	global_load_dwordx4 v[56:59], v[56:57], off
	s_cmp_lg_u32 s3, 0
	global_load_dwordx4 v[60:63], v[60:61], off
	s_cselect_b64 s[4:5], -1, 0
	s_cmp_eq_u32 s3, 0
	v_lshlrev_b32_e32 v80, 1, v96
	s_cbranch_scc1 .LBB0_107
	s_lshl_b32 s3, s20, 9
	v_ashrrev_i32_e32 v40, 5, v111
	v_ashrrev_i32_e32 v42, 5, v82
	v_ashrrev_i32_e32 v50, 5, v3
	v_ashrrev_i32_e32 v52, 5, v88
	v_readlane_b32 s12, v253, 24
	v_add_u32_e32 v40, s3, v40
	v_add_u32_e32 v42, s3, v42
	v_add_u32_e32 v50, s3, v50
	v_add_u32_e32 v52, s3, v52
	v_mov_b32_e32 v81, v1
	v_readlane_b32 s13, v253, 25
	v_ashrrev_i32_e32 v41, 31, v40
	v_ashrrev_i32_e32 v43, 31, v42
	v_ashrrev_i32_e32 v51, 31, v50
	v_ashrrev_i32_e32 v53, 31, v52
	v_lshl_add_u64 v[48:49], s[12:13], 0, v[80:81]
	v_lshlrev_b64 v[40:41], 9, v[40:41]
	v_lshlrev_b64 v[42:43], 9, v[42:43]
	v_lshlrev_b64 v[50:51], 9, v[50:51]
	v_lshlrev_b64 v[52:53], 9, v[52:53]
	v_lshl_add_u64 v[40:41], v[48:49], 0, v[40:41]
	v_lshl_add_u64 v[44:45], v[48:49], 0, v[42:43]
	v_lshl_add_u64 v[50:51], v[48:49], 0, v[50:51]
	v_lshl_add_u64 v[52:53], v[48:49], 0, v[52:53]
	global_load_dwordx4 v[40:43], v[40:41], off
	s_nop 0
	global_load_dwordx4 v[44:47], v[44:45], off
	s_nop 0
	global_load_dwordx4 v[48:51], v[50:51], off
	s_nop 0
	global_load_dwordx4 v[52:55], v[52:53], off

; #define LAS __attribute__((address_space(3)))
; __global__ void __launch_bounds__(512, 2) fwd_megakernel(Args a) {
;     extern __shared__ __attribute__((aligned(16))) unsigned char lds_raw[];
;     LAS unsigned char* lds = (LAS unsigned char*)lds_raw;
;     cg::grid_group grid = cg::this_grid();
;     int G = gridDim.x, bid = blockIdx.x;
;     if (threadIdx.x < 16) ((LAS unsigned*)(lds + LDS_CTL_OFF))[threadIdx.x] = 0u;
;     __syncthreads();
;     XcdBarrier bar = xcd_barrier_post((unsigned*)(a.ws + WS_CTL), (volatile LAS unsigned*)(lds + LDS_CTL_OFF));
	.amdhsa_kernel _Z14fwd_megakernel4Args
		.amdhsa_group_segment_fixed_size 0
		.amdhsa_private_segment_fixed_size 0
		.amdhsa_kernarg_size 392
		.amdhsa_user_sgpr_count 2
		.amdhsa_user_sgpr_dispatch_ptr 0
		.amdhsa_user_sgpr_queue_ptr 0
		.amdhsa_user_sgpr_kernarg_segment_ptr 1
		.amdhsa_user_sgpr_dispatch_id 0
		.amdhsa_user_sgpr_kernarg_preload_length 0
		.amdhsa_user_sgpr_kernarg_preload_offset 0
		.amdhsa_user_sgpr_private_segment_size 0
		.amdhsa_uses_dynamic_stack 0
		.amdhsa_enable_private_segment 0
		.amdhsa_system_sgpr_workgroup_id_x 1
		.amdhsa_system_sgpr_workgroup_id_y 0
		.amdhsa_system_sgpr_workgroup_id_z 0
		.amdhsa_system_sgpr_workgroup_info 0
		.amdhsa_system_vgpr_workitem_id 2
		.amdhsa_next_free_vgpr 256
		.amdhsa_next_free_sgpr 100
		.amdhsa_accum_offset 256
		.amdhsa_reserve_vcc 1
		.amdhsa_float_round_mode_32 0
		.amdhsa_float_round_mode_16_64 0
		.amdhsa_float_denorm_mode_32 3
		.amdhsa_float_denorm_mode_16_64 3
		.amdhsa_dx10_clamp 1
		.amdhsa_ieee_mode 1
		.amdhsa_fp16_overflow 0
		.amdhsa_tg_split 0
		.amdhsa_exception_fp_ieee_invalid_op 0
		.amdhsa_exception_fp_denorm_src 0
		.amdhsa_exception_fp_ieee_div_zero 0
		.amdhsa_exception_fp_ieee_overflow 0
		.amdhsa_exception_fp_ieee_underflow 0
		.amdhsa_exception_fp_ieee_inexact 0
		.amdhsa_exception_int_div_zero 0
	.end_amdhsa_kernel

; __global__ void __launch_bounds__(512, 2) fwd_megakernel(Args a) {
;     extern __shared__ __attribute__((aligned(16))) unsigned char lds_raw[];
amdhsa.kernels:
  - .agpr_count:     0
    .args:
      - .offset:         0
        .size:           136
        .value_kind:     by_value
      - .offset:         136
        .size:           4
        .value_kind:     hidden_block_count_x
      - .offset:         140
        .size:           4
        .value_kind:     hidden_block_count_y
      - .offset:         144
        .size:           4
        .value_kind:     hidden_block_count_z
      - .offset:         148
        .size:           2
        .value_kind:     hidden_group_size_x
      - .offset:         150
        .size:           2
        .value_kind:     hidden_group_size_y
      - .offset:         152
        .size:           2
        .value_kind:     hidden_group_size_z
      - .offset:         154
        .size:           2
        .value_kind:     hidden_remainder_x
      - .offset:         156
        .size:           2
        .value_kind:     hidden_remainder_y
      - .offset:         158
        .size:           2
        .value_kind:     hidden_remainder_z
      - .offset:         176
        .size:           8
        .value_kind:     hidden_global_offset_x
      - .offset:         184
        .size:           8
        .value_kind:     hidden_global_offset_y
      - .offset:         192
        .size:           8
        .value_kind:     hidden_global_offset_z
      - .offset:         200
        .size:           2
        .value_kind:     hidden_grid_dims
      - .offset:         224
        .size:           8
        .value_kind:     hidden_multigrid_sync_arg
      - .offset:         256
        .size:           4
        .value_kind:     hidden_dynamic_lds_size
    .group_segment_fixed_size: 0
    .kernarg_segment_align: 8
    .kernarg_segment_size: 392
    .language:       OpenCL C
    .language_version:
      - 2
      - 0
    .max_flat_workgroup_size: 512
    .name:           _Z14fwd_megakernel4Args
    .private_segment_fixed_size: 0
    .sgpr_count:     106
    .sgpr_spill_count: 451
    .symbol:         _Z14fwd_megakernel4Args.kd
    .uniform_work_group_size: 1
    .uses_dynamic_stack: false
    .vgpr_count:     256
    .vgpr_spill_count: 0
    .wavefront_size: 64
